# nt hint also on the final normalised-output stores (never re-read)
# baseline (speedup 1.0000x reference)
; __device__ __forceinline__ float bf_lo(unsigned w) { return __uint_as_float(w << 16); }
; __device__ __forceinline__ float bf_hi(unsigned w) { return __uint_as_float(w & 0xffff0000u); }
; __device__ __forceinline__ void final_phase(const Frame& F, KArgs* A_) {
;     ...
;         u32x4 q[3][4]; float rs[3] = {};
; #pragma unroll
;         for (int k = 0; k < 3; ++k) { const int r = r0 + k * NGW; if (r < MT) { rs[k] = lane < 32 ? part[(size_t)lane * MT + r] : 0.f;
; #pragma unroll
;             for (int j = 0; j < 4; ++j) q[k][j] = *(const u32x4*)(XB + (size_t)r * DM + (64 * j + lane) * 8); } }
;         asm volatile("" ::: "memory");
; #pragma unroll
;         for (int k = 0; k < 3; ++k) rs[k] = rsqrtf(wave_sum(rs[k]) * (1.0f / DM) + EPS);
; #pragma unroll
;         for (int k = 0; k < 3; ++k) { const int r = r0 + k * NGW; if (r < MT) {
; #pragma unroll
;             for (int j = 0; j < 4; ++j) { const int c = (64 * j + lane) * 8; const u32x4 w = q[k][j];
;                 const f32x4 a = (f32x4){bf_lo(w.x), bf_hi(w.x), bf_lo(w.y), bf_hi(w.y)} * rs[k] * gg[j][0], b = (f32x4){bf_lo(w.z), bf_hi(w.z), bf_lo(w.w), bf_hi(w.w)} * rs[k] * gg[j][1];
;                 *(f32x4*)(out + (size_t)r * DM + c) = a; *(f32x4*)(out + (size_t)r * DM + c + 4) = b; } } }
.LBB0_2283:
	v_and_b32_e32 v80, 64, v87
	v_add_u32_e32 v80, 64, v80
	v_xor_b32_e32 v82, 1, v87
	v_cmp_lt_i32_e32 vcc, v82, v80
	v_xor_b32_e32 v110, 4, v87
	v_xor_b32_e32 v112, 16, v87
	v_cndmask_b32_e32 v82, v87, v82, vcc
	v_lshlrev_b32_e32 v83, 2, v82
	v_xor_b32_e32 v82, 2, v87
	v_cmp_lt_i32_e32 vcc, v82, v80
	ds_bpermute_b32 v111, v83, v85
	v_xor_b32_e32 v113, 32, v87
	v_cndmask_b32_e32 v82, v87, v82, vcc
	v_lshlrev_b32_e32 v109, 2, v82
	ds_bpermute_b32 v82, v83, v84
	s_waitcnt vmcnt(4)
	ds_bpermute_b32 v83, v83, v86
	s_waitcnt lgkmcnt(2)
	v_add_f32_e32 v111, v85, v111
	v_mov_b32_e32 v85, v86
	v_cmp_lt_i32_e32 vcc, v110, v80
	v_xor_b32_e32 v86, 8, v87
	s_waitcnt lgkmcnt(0)
	v_pk_add_f32 v[82:83], v[84:85], v[82:83]
	ds_bpermute_b32 v84, v109, v82
	ds_bpermute_b32 v85, v109, v83
	v_cndmask_b32_e32 v110, v87, v110, vcc
	v_lshlrev_b32_e32 v110, 2, v110
	v_cmp_lt_i32_e32 vcc, v86, v80
	ds_bpermute_b32 v109, v109, v111
	s_waitcnt lgkmcnt(1)
	v_pk_add_f32 v[82:83], v[82:83], v[84:85]
	ds_bpermute_b32 v84, v110, v82
	ds_bpermute_b32 v85, v110, v83
	v_cndmask_b32_e32 v86, v87, v86, vcc
	v_lshlrev_b32_e32 v86, 2, v86
	v_cmp_lt_i32_e32 vcc, v112, v80
	s_waitcnt lgkmcnt(2)
	v_add_f32_e32 v109, v111, v109
	s_waitcnt lgkmcnt(0)
	v_pk_add_f32 v[82:83], v[82:83], v[84:85]
	ds_bpermute_b32 v84, v86, v82
	ds_bpermute_b32 v85, v86, v83
	v_cndmask_b32_e32 v112, v87, v112, vcc
	v_lshlrev_b32_e32 v112, 2, v112
	ds_bpermute_b32 v110, v110, v109
	v_cmp_lt_i32_e32 vcc, v113, v80
	s_waitcnt lgkmcnt(1)
	v_pk_add_f32 v[82:83], v[82:83], v[84:85]
	ds_bpermute_b32 v84, v112, v82
	ds_bpermute_b32 v85, v112, v83
	v_cndmask_b32_e32 v80, v87, v113, vcc
	v_lshlrev_b32_e32 v111, 2, v80
	s_waitcnt lgkmcnt(2)
	v_add_f32_e32 v80, v109, v110
	ds_bpermute_b32 v86, v86, v80
	s_waitcnt lgkmcnt(1)
	v_pk_add_f32 v[82:83], v[82:83], v[84:85]
	ds_bpermute_b32 v84, v111, v82
	ds_bpermute_b32 v85, v111, v83
	s_waitcnt vmcnt(3)
	v_lshlrev_b32_e32 v110, 16, v76
	s_waitcnt lgkmcnt(2)
	v_add_f32_e32 v80, v80, v86
	ds_bpermute_b32 v86, v112, v80
	v_lshl_add_u64 v[114:115], s[12:13], 0, v[90:91]
	s_waitcnt lgkmcnt(1)
	v_pk_add_f32 v[82:83], v[82:83], v[84:85]
	s_waitcnt lgkmcnt(0)
	v_add_f32_e32 v80, v80, v86
	v_pk_fma_f32 v[82:83], v[82:83], s[18:19], v[108:109] op_sel_hi:[1,0,0]
	s_nop 0
	v_mul_f32_e32 v84, 0x4b800000, v82
	v_cmp_gt_f32_e32 vcc, s9, v82
	v_cmp_gt_f32_e64 s[2:3], s9, v83
	s_nop 0
	v_cndmask_b32_e32 v82, v82, v84, vcc
	v_rsq_f32_e32 v84, v82
	ds_bpermute_b32 v82, v111, v80
	v_and_b32_e32 v111, 0xffff0000, v76
	v_lshlrev_b32_e32 v76, 16, v77
	v_mul_f32_e32 v85, 0x45800000, v84
	v_cndmask_b32_e32 v84, v84, v85, vcc
	v_and_b32_e32 v77, 0xffff0000, v77
	v_pk_mul_f32 v[76:77], v[84:85], v[76:77] op_sel_hi:[0,1]
	v_pk_mul_f32 v[112:113], v[6:7], v[76:77]
	v_lshlrev_b32_e32 v76, 16, v78
	v_and_b32_e32 v77, 0xffff0000, v78
	v_pk_mul_f32 v[110:111], v[84:85], v[110:111] op_sel_hi:[0,1]
	v_lshlrev_b32_e32 v78, 16, v79
	v_and_b32_e32 v79, 0xffff0000, v79
	v_pk_mul_f32 v[76:77], v[84:85], v[76:77] op_sel_hi:[0,1]
	v_pk_mul_f32 v[110:111], v[4:5], v[110:111]
	v_pk_mul_f32 v[78:79], v[84:85], v[78:79] op_sel_hi:[0,1]
	v_pk_mul_f32 v[76:77], v[0:1], v[76:77]
	v_pk_mul_f32 v[78:79], v[2:3], v[78:79]
	global_store_dwordx4 v[114:115], v[110:113], off nt
	global_store_dwordx4 v[114:115], v[76:79], off offset:16 nt
	s_andn2_b64 vcc, exec, s[26:27]
	s_waitcnt vmcnt(4)
	v_lshlrev_b32_e32 v76, 16, v72
	v_and_b32_e32 v77, 0xffff0000, v72
	v_lshlrev_b32_e32 v72, 16, v73
	v_and_b32_e32 v73, 0xffff0000, v73
	v_pk_mul_f32 v[72:73], v[84:85], v[72:73] op_sel_hi:[0,1]
	v_pk_mul_f32 v[78:79], v[14:15], v[72:73]
	v_lshlrev_b32_e32 v72, 16, v74
	v_and_b32_e32 v73, 0xffff0000, v74
	v_pk_mul_f32 v[76:77], v[84:85], v[76:77] op_sel_hi:[0,1]
	v_lshlrev_b32_e32 v74, 16, v75
	v_and_b32_e32 v75, 0xffff0000, v75
	v_pk_mul_f32 v[72:73], v[84:85], v[72:73] op_sel_hi:[0,1]
	v_pk_mul_f32 v[76:77], v[12:13], v[76:77]
	v_pk_mul_f32 v[74:75], v[84:85], v[74:75] op_sel_hi:[0,1]
	v_pk_mul_f32 v[72:73], v[8:9], v[72:73]
	v_pk_mul_f32 v[74:75], v[10:11], v[74:75]
	global_store_dwordx4 v[114:115], v[76:79], off offset:2048 nt
	global_store_dwordx4 v[114:115], v[72:75], off offset:2064 nt
	s_nop 0
	v_lshl_add_u64 v[76:77], s[12:13], 0, v[94:95]
	s_waitcnt vmcnt(5)
	v_lshlrev_b32_e32 v72, 16, v68
	v_and_b32_e32 v73, 0xffff0000, v68
	v_lshlrev_b32_e32 v68, 16, v69
	v_and_b32_e32 v69, 0xffff0000, v69
	v_pk_mul_f32 v[68:69], v[84:85], v[68:69] op_sel_hi:[0,1]
	v_pk_mul_f32 v[74:75], v[22:23], v[68:69]
	v_lshlrev_b32_e32 v68, 16, v70
	v_and_b32_e32 v69, 0xffff0000, v70
	v_pk_mul_f32 v[72:73], v[84:85], v[72:73] op_sel_hi:[0,1]
	v_lshlrev_b32_e32 v70, 16, v71
	v_and_b32_e32 v71, 0xffff0000, v71
	v_pk_mul_f32 v[68:69], v[84:85], v[68:69] op_sel_hi:[0,1]
	v_pk_mul_f32 v[72:73], v[20:21], v[72:73]
	v_pk_mul_f32 v[70:71], v[84:85], v[70:71] op_sel_hi:[0,1]
	v_pk_mul_f32 v[68:69], v[16:17], v[68:69]
	v_pk_mul_f32 v[70:71], v[18:19], v[70:71]
	global_store_dwordx4 v[76:77], v[72:75], off nt
	global_store_dwordx4 v[76:77], v[68:71], off offset:16 nt
	s_nop 0
	v_lshl_add_u64 v[72:73], s[12:13], 0, v[98:99]
	s_waitcnt vmcnt(6)
	v_lshlrev_b32_e32 v68, 16, v64
	v_and_b32_e32 v69, 0xffff0000, v64
	v_lshlrev_b32_e32 v64, 16, v65
	v_and_b32_e32 v65, 0xffff0000, v65
	v_pk_mul_f32 v[64:65], v[84:85], v[64:65] op_sel_hi:[0,1]
	v_pk_mul_f32 v[70:71], v[30:31], v[64:65]
	v_lshlrev_b32_e32 v64, 16, v66
	v_and_b32_e32 v65, 0xffff0000, v66
	v_lshlrev_b32_e32 v66, 16, v67
	v_and_b32_e32 v67, 0xffff0000, v67
	v_pk_mul_f32 v[68:69], v[84:85], v[68:69] op_sel_hi:[0,1]
	v_pk_mul_f32 v[64:65], v[84:85], v[64:65] op_sel_hi:[0,1]
	v_pk_mul_f32 v[66:67], v[84:85], v[66:67] op_sel_hi:[0,1]
	v_pk_mul_f32 v[68:69], v[28:29], v[68:69]
	v_pk_mul_f32 v[66:67], v[26:27], v[66:67]
	v_pk_mul_f32 v[64:65], v[24:25], v[64:65]
	global_store_dwordx4 v[72:73], v[68:71], off nt
	global_store_dwordx4 v[72:73], v[64:67], off offset:16 nt
	s_cbranch_vccnz .LBB0_2285
; __device__ __forceinline__ float bf_lo(unsigned w) { return __uint_as_float(w << 16); }
; __device__ __forceinline__ float bf_hi(unsigned w) { return __uint_as_float(w & 0xffff0000u); }
; __device__ __forceinline__ void final_phase(const Frame& F, KArgs* A_) {
;     ...
;         for (int k = 0; k < 3; ++k) rs[k] = rsqrtf(wave_sum(rs[k]) * (1.0f / DM) + EPS);
; #pragma unroll
;         for (int k = 0; k < 3; ++k) { const int r = r0 + k * NGW; if (r < MT) {
; #pragma unroll
;             for (int j = 0; j < 4; ++j) { const int c = (64 * j + lane) * 8; const u32x4 w = q[k][j];
;                 const f32x4 a = (f32x4){bf_lo(w.x), bf_hi(w.x), bf_lo(w.y), bf_hi(w.y)} * rs[k] * gg[j][0], b = (f32x4){bf_lo(w.z), bf_hi(w.z), bf_lo(w.w), bf_hi(w.w)} * rs[k] * gg[j][1];
;                 *(f32x4*)(out + (size_t)r * DM + c) = a; *(f32x4*)(out + (size_t)r * DM + c + 4) = b; } } }
	s_waitcnt lgkmcnt(0)
	v_add_f32_e32 v64, v80, v82
	v_fmamk_f32 v64, v64, 0x3a000000, v108
	v_mul_f32_e32 v65, 0x4b800000, v64
	v_cmp_gt_f32_e32 vcc, s9, v64
	s_ashr_i32 s25, s24, 31
	s_lshl_b64 s[24:25], s[24:25], 13
	v_cndmask_b32_e32 v64, v64, v65, vcc
	v_rsq_f32_e32 v64, v64
	s_add_u32 s24, s4, s24
	v_lshlrev_b32_e32 v66, 16, v49
	v_and_b32_e32 v67, 0xffff0000, v49
	v_mul_f32_e32 v65, 0x45800000, v64
	v_cndmask_b32_e32 v72, v64, v65, vcc
	v_lshlrev_b32_e32 v64, 16, v48
	v_and_b32_e32 v65, 0xffff0000, v48
	s_addc_u32 s25, s5, s25
	v_pk_mul_f32 v[64:65], v[72:73], v[64:65] op_sel_hi:[0,1]
	v_pk_mul_f32 v[66:67], v[72:73], v[66:67] op_sel_hi:[0,1]
	v_lshlrev_b32_e32 v68, 16, v50
	v_and_b32_e32 v69, 0xffff0000, v50
	v_lshlrev_b32_e32 v70, 16, v51
	v_and_b32_e32 v71, 0xffff0000, v51
	v_pk_mul_f32 v[66:67], v[6:7], v[66:67]
	v_pk_mul_f32 v[64:65], v[4:5], v[64:65]
	v_pk_mul_f32 v[68:69], v[72:73], v[68:69] op_sel_hi:[0,1]
	v_pk_mul_f32 v[70:71], v[72:73], v[70:71] op_sel_hi:[0,1]
	v_lshl_add_u64 v[74:75], v[88:89], 2, s[24:25]
	v_pk_mul_f32 v[70:71], v[2:3], v[70:71]
	v_pk_mul_f32 v[68:69], v[0:1], v[68:69]
	global_store_dwordx4 v[74:75], v[64:67], off nt
	global_store_dwordx4 v[74:75], v[68:71], off offset:16 nt
	s_nop 0
	v_lshlrev_b32_e32 v64, 16, v52
	v_and_b32_e32 v65, 0xffff0000, v52
	v_lshlrev_b32_e32 v66, 16, v53
	v_and_b32_e32 v67, 0xffff0000, v53
	v_pk_mul_f32 v[64:65], v[72:73], v[64:65] op_sel_hi:[0,1]
	v_pk_mul_f32 v[66:67], v[72:73], v[66:67] op_sel_hi:[0,1]
	v_lshlrev_b32_e32 v68, 16, v54
	v_and_b32_e32 v69, 0xffff0000, v54
	v_lshlrev_b32_e32 v70, 16, v55
	v_and_b32_e32 v71, 0xffff0000, v55
	v_pk_mul_f32 v[66:67], v[14:15], v[66:67]
	v_pk_mul_f32 v[64:65], v[12:13], v[64:65]
	v_pk_mul_f32 v[68:69], v[72:73], v[68:69] op_sel_hi:[0,1]
	v_pk_mul_f32 v[70:71], v[72:73], v[70:71] op_sel_hi:[0,1]
	v_pk_mul_f32 v[70:71], v[10:11], v[70:71]
	v_pk_mul_f32 v[68:69], v[8:9], v[68:69]
	global_store_dwordx4 v[74:75], v[64:67], off offset:2048 nt
	global_store_dwordx4 v[74:75], v[68:71], off offset:2064 nt
	v_lshl_add_u64 v[74:75], v[92:93], 2, s[24:25]
	v_lshlrev_b32_e32 v64, 16, v56
	v_and_b32_e32 v65, 0xffff0000, v56
	v_lshlrev_b32_e32 v66, 16, v57
	v_and_b32_e32 v67, 0xffff0000, v57
	v_pk_mul_f32 v[64:65], v[72:73], v[64:65] op_sel_hi:[0,1]
	v_pk_mul_f32 v[66:67], v[72:73], v[66:67] op_sel_hi:[0,1]
	v_lshlrev_b32_e32 v68, 16, v58
	v_and_b32_e32 v69, 0xffff0000, v58
	v_lshlrev_b32_e32 v70, 16, v59
	v_and_b32_e32 v71, 0xffff0000, v59
	v_pk_mul_f32 v[66:67], v[22:23], v[66:67]
	v_pk_mul_f32 v[64:65], v[20:21], v[64:65]
	v_pk_mul_f32 v[68:69], v[72:73], v[68:69] op_sel_hi:[0,1]
	v_pk_mul_f32 v[70:71], v[72:73], v[70:71] op_sel_hi:[0,1]
	v_pk_mul_f32 v[70:71], v[18:19], v[70:71]
	v_pk_mul_f32 v[68:69], v[16:17], v[68:69]
	global_store_dwordx4 v[74:75], v[64:67], off nt
	global_store_dwordx4 v[74:75], v[68:71], off offset:16 nt
	s_nop 0
	v_lshlrev_b32_e32 v64, 16, v60
	v_and_b32_e32 v65, 0xffff0000, v60
	v_lshlrev_b32_e32 v66, 16, v61
	v_and_b32_e32 v67, 0xffff0000, v61
	v_pk_mul_f32 v[64:65], v[72:73], v[64:65] op_sel_hi:[0,1]
	v_pk_mul_f32 v[66:67], v[72:73], v[66:67] op_sel_hi:[0,1]
	v_lshlrev_b32_e32 v68, 16, v62
	v_and_b32_e32 v69, 0xffff0000, v62
	v_lshlrev_b32_e32 v70, 16, v63
	v_and_b32_e32 v71, 0xffff0000, v63
	v_pk_mul_f32 v[66:67], v[30:31], v[66:67]
	v_pk_mul_f32 v[64:65], v[28:29], v[64:65]
	v_pk_mul_f32 v[68:69], v[72:73], v[68:69] op_sel_hi:[0,1]
	v_pk_mul_f32 v[70:71], v[72:73], v[70:71] op_sel_hi:[0,1]
	v_lshl_add_u64 v[72:73], v[96:97], 2, s[24:25]
	v_pk_mul_f32 v[70:71], v[26:27], v[70:71]
	v_pk_mul_f32 v[68:69], v[24:25], v[68:69]
	global_store_dwordx4 v[72:73], v[64:67], off nt
	global_store_dwordx4 v[72:73], v[68:71], off offset:16 nt
; __device__ __forceinline__ float bf_lo(unsigned w) { return __uint_as_float(w << 16); }
; __device__ __forceinline__ float bf_hi(unsigned w) { return __uint_as_float(w & 0xffff0000u); }
; __device__ __forceinline__ void final_phase(const Frame& F, KArgs* A_) {
;     ...
;         for (int k = 0; k < 3; ++k) rs[k] = rsqrtf(wave_sum(rs[k]) * (1.0f / DM) + EPS);
; #pragma unroll
;         for (int k = 0; k < 3; ++k) { const int r = r0 + k * NGW; if (r < MT) {
; #pragma unroll
;             for (int j = 0; j < 4; ++j) { const int c = (64 * j + lane) * 8; const u32x4 w = q[k][j];
;                 const f32x4 a = (f32x4){bf_lo(w.x), bf_hi(w.x), bf_lo(w.y), bf_hi(w.y)} * rs[k] * gg[j][0], b = (f32x4){bf_lo(w.z), bf_hi(w.z), bf_lo(w.w), bf_hi(w.w)} * rs[k] * gg[j][1];
;                 *(f32x4*)(out + (size_t)r * DM + c) = a; *(f32x4*)(out + (size_t)r * DM + c + 4) = b; } } }
.LBB0_2285:
	s_andn2_b64 vcc, exec, s[22:23]
	s_cbranch_vccnz .LBB0_2272
	v_mul_f32_e32 v64, 0x4b800000, v83
	v_cndmask_b32_e64 v64, v83, v64, s[2:3]
	v_rsq_f32_e32 v64, v64
	s_ashr_i32 s21, s20, 31
	s_lshl_b64 s[20:21], s[20:21], 13
	s_add_u32 s20, s4, s20
	v_mul_f32_e32 v65, 0x45800000, v64
	v_cndmask_b32_e64 v72, v64, v65, s[2:3]
	v_lshlrev_b32_e32 v64, 16, v44
	v_and_b32_e32 v65, 0xffff0000, v44
	v_lshlrev_b32_e32 v66, 16, v45
	v_and_b32_e32 v67, 0xffff0000, v45
	s_addc_u32 s21, s5, s21
	v_pk_mul_f32 v[64:65], v[72:73], v[64:65] op_sel_hi:[0,1]
	v_pk_mul_f32 v[66:67], v[72:73], v[66:67] op_sel_hi:[0,1]
	v_lshlrev_b32_e32 v68, 16, v46
	v_and_b32_e32 v69, 0xffff0000, v46
	v_lshlrev_b32_e32 v70, 16, v47
	v_and_b32_e32 v71, 0xffff0000, v47
	v_pk_mul_f32 v[66:67], v[6:7], v[66:67]
	v_pk_mul_f32 v[64:65], v[4:5], v[64:65]
	v_pk_mul_f32 v[68:69], v[72:73], v[68:69] op_sel_hi:[0,1]
	v_pk_mul_f32 v[70:71], v[72:73], v[70:71] op_sel_hi:[0,1]
	v_lshl_add_u64 v[74:75], v[88:89], 2, s[20:21]
	v_pk_mul_f32 v[70:71], v[2:3], v[70:71]
	v_pk_mul_f32 v[68:69], v[0:1], v[68:69]
	global_store_dwordx4 v[74:75], v[64:67], off nt
	global_store_dwordx4 v[74:75], v[68:71], off offset:16 nt
	s_nop 0
	v_lshlrev_b32_e32 v64, 16, v40
	v_and_b32_e32 v65, 0xffff0000, v40
	v_lshlrev_b32_e32 v66, 16, v41
	v_and_b32_e32 v67, 0xffff0000, v41
	v_pk_mul_f32 v[64:65], v[72:73], v[64:65] op_sel_hi:[0,1]
	v_pk_mul_f32 v[66:67], v[72:73], v[66:67] op_sel_hi:[0,1]
	v_lshlrev_b32_e32 v68, 16, v42
	v_and_b32_e32 v69, 0xffff0000, v42
	v_lshlrev_b32_e32 v70, 16, v43
	v_and_b32_e32 v71, 0xffff0000, v43
	v_pk_mul_f32 v[66:67], v[14:15], v[66:67]
	v_pk_mul_f32 v[64:65], v[12:13], v[64:65]
	v_pk_mul_f32 v[68:69], v[72:73], v[68:69] op_sel_hi:[0,1]
	v_pk_mul_f32 v[70:71], v[72:73], v[70:71] op_sel_hi:[0,1]
	v_pk_mul_f32 v[70:71], v[10:11], v[70:71]
	v_pk_mul_f32 v[68:69], v[8:9], v[68:69]
	global_store_dwordx4 v[74:75], v[64:67], off offset:2048 nt
	global_store_dwordx4 v[74:75], v[68:71], off offset:2064 nt
	v_lshl_add_u64 v[74:75], v[92:93], 2, s[20:21]
	v_lshlrev_b32_e32 v64, 16, v36
	v_and_b32_e32 v65, 0xffff0000, v36
	v_lshlrev_b32_e32 v66, 16, v37
	v_and_b32_e32 v67, 0xffff0000, v37
	v_pk_mul_f32 v[64:65], v[72:73], v[64:65] op_sel_hi:[0,1]
	v_pk_mul_f32 v[66:67], v[72:73], v[66:67] op_sel_hi:[0,1]
	v_lshlrev_b32_e32 v68, 16, v38
	v_and_b32_e32 v69, 0xffff0000, v38
	v_lshlrev_b32_e32 v70, 16, v39
	v_and_b32_e32 v71, 0xffff0000, v39
	v_pk_mul_f32 v[66:67], v[22:23], v[66:67]
	v_pk_mul_f32 v[64:65], v[20:21], v[64:65]
	v_pk_mul_f32 v[68:69], v[72:73], v[68:69] op_sel_hi:[0,1]
	v_pk_mul_f32 v[70:71], v[72:73], v[70:71] op_sel_hi:[0,1]
	v_pk_mul_f32 v[70:71], v[18:19], v[70:71]
	v_pk_mul_f32 v[68:69], v[16:17], v[68:69]
	global_store_dwordx4 v[74:75], v[64:67], off nt
	global_store_dwordx4 v[74:75], v[68:71], off offset:16 nt
	s_nop 0
	v_lshlrev_b32_e32 v64, 16, v32
	v_and_b32_e32 v65, 0xffff0000, v32
	v_lshlrev_b32_e32 v66, 16, v33
	v_and_b32_e32 v67, 0xffff0000, v33
	v_pk_mul_f32 v[64:65], v[72:73], v[64:65] op_sel_hi:[0,1]
	v_pk_mul_f32 v[66:67], v[72:73], v[66:67] op_sel_hi:[0,1]
	v_lshlrev_b32_e32 v68, 16, v34
	v_and_b32_e32 v69, 0xffff0000, v34
	v_lshlrev_b32_e32 v70, 16, v35
	v_and_b32_e32 v71, 0xffff0000, v35
	v_pk_mul_f32 v[66:67], v[30:31], v[66:67]
	v_pk_mul_f32 v[64:65], v[28:29], v[64:65]
	v_pk_mul_f32 v[68:69], v[72:73], v[68:69] op_sel_hi:[0,1]
	v_pk_mul_f32 v[70:71], v[72:73], v[70:71] op_sel_hi:[0,1]
	v_lshl_add_u64 v[72:73], v[96:97], 2, s[20:21]
	v_pk_mul_f32 v[70:71], v[26:27], v[70:71]
	v_pk_mul_f32 v[68:69], v[24:25], v[68:69]
	global_store_dwordx4 v[72:73], v[64:67], off nt
	global_store_dwordx4 v[72:73], v[68:71], off offset:16 nt
	s_branch .LBB0_2272
